# attention: next unit's first K/V tiles (LDS-DMA) and Q rows prefetched during the tail of the current unit
# baseline (speedup 1.0000x reference)
.Lp3_pre:
	global_load_dword v1, v0, s[20:21]
	global_load_dword v2, v0, s[22:23]
	v_mbcnt_hi_u32_b32 v0, -1, v218
	v_and_b32_e32 v3, 64, v0
	v_xor_b32_e32 v4, 1, v0
	v_add_u32_e32 v3, 64, v3
	v_cmp_lt_i32_e32 vcc, v4, v3
	v_xor_b32_e32 v5, 2, v0
	v_xor_b32_e32 v6, 4, v0
	v_cndmask_b32_e32 v4, v0, v4, vcc
	v_lshlrev_b32_e32 v142, 2, v4
	v_cmp_lt_i32_e32 vcc, v5, v3
	v_xor_b32_e32 v7, 8, v0
	v_xor_b32_e32 v8, 16, v0
	v_cndmask_b32_e32 v5, v0, v5, vcc
	v_lshlrev_b32_e32 v143, 2, v5
	v_cmp_lt_i32_e32 vcc, v6, v3
	v_xor_b32_e32 v9, 32, v0
	s_add_u32 s0, s42, 0x11800000
	v_cndmask_b32_e32 v6, v0, v6, vcc
	v_lshlrev_b32_e32 v144, 2, v6
	v_cmp_lt_i32_e32 vcc, v7, v3
	s_addc_u32 s1, s43, 0
	v_mov_b32_e32 v99, 0
	v_cndmask_b32_e32 v6, v0, v7, vcc
	v_lshlrev_b32_e32 v145, 2, v6
	v_cmp_lt_i32_e32 vcc, v8, v3
	s_mov_b32 s17, 0
	s_cmpk_lt_i32 s75, 0xc00
	v_cndmask_b32_e32 v6, v0, v8, vcc
	v_lshlrev_b32_e32 v146, 2, v6
	v_cmp_lt_i32_e32 vcc, v9, v3
	s_waitcnt vmcnt(1)
	v_and_b32_e32 v4, 0x7fffffff, v1
	s_waitcnt vmcnt(0)
	v_and_b32_e32 v10, 0x7fffffff, v2
	ds_bpermute_b32 v4, v142, v4
	ds_bpermute_b32 v10, v142, v10
	v_max_f32_e64 v1, |v1|, |v1|
	v_max_f32_e64 v2, |v2|, |v2|
	v_cndmask_b32_e32 v0, v0, v9, vcc
	s_waitcnt lgkmcnt(1)
	v_max_f32_e32 v4, v4, v4
	s_waitcnt lgkmcnt(0)
	v_max_f32_e32 v5, v10, v10
	v_max_f32_e32 v1, v1, v4
	v_max_f32_e32 v2, v2, v5
	ds_bpermute_b32 v4, v143, v1
	ds_bpermute_b32 v5, v143, v2
	v_lshlrev_b32_e32 v147, 2, v0
	s_waitcnt lgkmcnt(1)
	v_max_f32_e32 v4, v4, v4
	s_waitcnt lgkmcnt(0)
	v_max_f32_e32 v5, v5, v5
	v_max_f32_e32 v1, v1, v4
	v_max_f32_e32 v2, v2, v5
	ds_bpermute_b32 v4, v144, v1
	ds_bpermute_b32 v5, v144, v2
	s_waitcnt lgkmcnt(1)
	v_max_f32_e32 v4, v4, v4
	s_waitcnt lgkmcnt(0)
	v_max_f32_e32 v5, v5, v5
	v_max_f32_e32 v1, v1, v4
	v_max_f32_e32 v2, v2, v5
	ds_bpermute_b32 v4, v145, v1
	ds_bpermute_b32 v5, v145, v2
	s_waitcnt lgkmcnt(1)
	v_max_f32_e32 v4, v4, v4
	s_waitcnt lgkmcnt(0)
	v_max_f32_e32 v5, v5, v5
	v_max_f32_e32 v1, v1, v4
	v_max_f32_e32 v2, v2, v5
	ds_bpermute_b32 v4, v146, v1
	ds_bpermute_b32 v5, v146, v2
	s_waitcnt lgkmcnt(1)
	v_max_f32_e32 v0, v4, v4
	s_waitcnt lgkmcnt(0)
	v_max_f32_e32 v3, v5, v5
	v_max_f32_e32 v0, v1, v0
	v_max_f32_e32 v1, v2, v3
	ds_bpermute_b32 v2, v147, v0
	ds_bpermute_b32 v3, v147, v1
	s_waitcnt lgkmcnt(1)
	v_max_f32_e32 v2, v2, v2
	s_waitcnt lgkmcnt(0)
	v_max_f32_e32 v3, v3, v3
	v_max_f32_e32 v0, v0, v2
	v_max_f32_e32 v1, v1, v3
	v_mul_f32_e32 v0, 0x4138aa3b, v0
	v_mul_f32_e32 v0, v0, v1
	s_nop 0
	v_readfirstlane_b32 s2, v0
	s_cbranch_scc0 .LBB0_320
	v_mov_b32_e32 v0, 0x42200000
	s_lshl_b32 s4, s74, 12
	v_lshrrev_b32_e32 v148, 3, v191
	v_cmp_nlt_f32_e64 s[2:3], s2, v0
	s_lshl_b32 s18, s74, 5
	s_add_i32 s4, s4, 0
	s_mov_b32 s19, s17
	v_xor_b32_e32 v0, v148, v191
	s_add_i32 s11, s4, 0x10000
	s_lshl_b64 s[4:5], s[18:19], 2
	v_lshlrev_b32_e32 v0, 4, v0
	s_add_u32 s4, s26, s4
	v_and_b32_e32 v0, 48, v0
	v_lshlrev_b32_e32 v2, 7, v148
	v_xor_b32_e32 v3, v212, v191
	s_movk_i32 s6, 0x70
	s_addc_u32 s5, s27, s5
	v_lshlrev_b32_e32 v98, 4, v197
	v_add_u32_e32 v4, s11, v0
	v_and_b32_e32 v0, 4, v191
	v_and_or_b32 v2, v3, s6, v2
	v_bfe_u32 v3, v191, 1, 3
	v_bitop3_b32 v14, v197, v219, 7 bitop3:0x78
	v_lshl_add_u64 v[100:101], s[4:5], 0, v[98:99]
	v_cmp_eq_u32_e64 s[4:5], 0, v0
	v_and_b32_e32 v0, 56, v220
	v_readlane_b32 s8, v254, 22
	v_lshlrev_b32_e32 v156, 4, v14
	v_bitop3_b32 v14, v197, v3, 2 bitop3:0x36
	v_add_u32_e32 v150, 0, v2
	v_lshlrev_b32_e32 v2, 7, v189
	v_lshlrev_b32_e32 v98, 1, v0
	v_readlane_b32 s9, v254, 23
	v_lshlrev_b32_e32 v157, 4, v14
	v_bitop3_b32 v14, v197, v3, 4 bitop3:0x36
	v_bitop3_b32 v3, v197, v3, 6 bitop3:0x36
	v_add_u32_e32 v151, 0, v2
	v_add_u32_e32 v5, s11, v2
	v_and_b32_e32 v2, 15, v191
	v_lshl_add_u64 v[102:103], s[8:9], 0, v[98:99]
	v_readlane_b32 s8, v254, 5
	v_lshlrev_b32_e32 v159, 4, v3
	v_bitop3_b32 v3, v197, v191, 15 bitop3:0x78
	v_mov_b32_e32 v195, v99
	v_readlane_b32 s9, v254, 6
	v_lshlrev_b32_e32 v158, 4, v14
	v_lshlrev_b32_e32 v14, 3, v3
	v_bitop3_b32 v3, v197, v2, 2 bitop3:0x36
	v_lshl_add_u64 v[106:107], s[8:9], 0, v[194:195]
	s_mov_b64 s[8:9], 0x1000
	v_lshlrev_b32_e32 v15, 3, v3
	v_bitop3_b32 v3, v197, v2, 4 bitop3:0x36
	v_lshl_add_u64 v[108:109], v[106:107], 0, s[8:9]
	s_mov_b64 s[8:9], 0x1400
	v_lshlrev_b32_e32 v16, 3, v3
	v_bitop3_b32 v3, v197, v2, 6 bitop3:0x36
	v_lshl_add_u64 v[110:111], v[106:107], 0, s[8:9]
	s_mov_b64 s[8:9], 0x1800
	v_lshlrev_b32_e32 v17, 3, v3
	v_bitop3_b32 v3, v197, v2, 8 bitop3:0x36
	v_lshl_add_u64 v[112:113], v[106:107], 0, s[8:9]
	s_mov_b64 s[8:9], 0x1c00
	v_lshlrev_b32_e32 v18, 3, v3
	v_bitop3_b32 v3, v197, v2, 10 bitop3:0x36
	v_lshrrev_b32_e32 v152, 3, v190
	v_lshl_add_u64 v[114:115], v[106:107], 0, s[8:9]
	s_mov_b64 s[8:9], 0x2000
	v_lshlrev_b32_e32 v19, 3, v3
	v_bitop3_b32 v3, v197, v2, 12 bitop3:0x36
	v_bitop3_b32 v2, v197, v2, 14 bitop3:0x36
	v_lshl_add_u64 v[116:117], v[106:107], 0, s[8:9]
	s_mov_b64 s[8:9], 0x2400
	v_lshlrev_b32_e32 v21, 3, v2
	v_and_b32_e32 v2, 0x70, v212
	v_or_b32_e32 v160, 8, v152
	v_lshl_add_u64 v[118:119], v[106:107], 0, s[8:9]
	s_mov_b64 s[8:9], 0x2800
	v_bitop3_b32 v23, v191, v2, 48 bitop3:0x6c
	v_lshrrev_b32_e32 v2, 1, v160
	v_lshl_add_u64 v[120:121], v[106:107], 0, s[8:9]
	s_mov_b64 s[8:9], 0x2c00
	v_xor_b32_e32 v2, v2, v191
	v_lshl_add_u64 v[122:123], v[106:107], 0, s[8:9]
	s_mov_b64 s[8:9], 0x3000
	v_lshlrev_b32_e32 v2, 4, v2
	v_or_b32_e32 v162, 24, v152
	v_lshl_add_u64 v[124:125], v[106:107], 0, s[8:9]
	s_mov_b64 s[8:9], 0x3400
	v_and_b32_e32 v25, 0x70, v2
	v_lshrrev_b32_e32 v2, 1, v162
	v_lshl_add_u64 v[126:127], v[106:107], 0, s[8:9]
	s_mov_b64 s[8:9], 0x3800
	v_xor_b32_e32 v2, v2, v191
	v_and_b32_e32 v6, 8, v191
	v_lshl_add_u64 v[104:105], s[0:1], 0, v[98:99]
	v_lshl_add_u64 v[128:129], v[106:107], 0, s[8:9]
	s_mov_b64 s[8:9], 0x3c00
	v_lshlrev_b32_e32 v2, 4, v2
	v_lshlrev_b32_e32 v98, 4, v217
	v_cmp_eq_u32_e64 s[6:7], 0, v6
	v_lshl_add_u64 v[130:131], v[106:107], 0, s[8:9]
	v_bitop3_b32 v6, v197, v191, 7 bitop3:0x78
	v_bitop3_b32 v7, v197, v217, 2 bitop3:0x36
	v_bitop3_b32 v8, v197, v217, 4 bitop3:0x36
	v_bitop3_b32 v9, v197, v217, 6 bitop3:0x36
	v_or_b32_e32 v153, 16, v193
	v_or_b32_e32 v154, 32, v193
	v_or_b32_e32 v155, 48, v193
	v_lshlrev_b32_e32 v20, 3, v3
	v_or_b32_e32 v161, 16, v152
	v_and_b32_e32 v28, 0x70, v2
	v_lshl_add_u64 v[2:3], s[42:43], 0, v[98:99]
	s_mov_b64 s[8:9], 0xac00100
	v_lshl_add_u32 v1, v189, 6, s11
	v_lshlrev_b32_e32 v6, 3, v6
	v_lshlrev_b32_e32 v7, 3, v7
	v_lshlrev_b32_e32 v8, 3, v8
	v_lshlrev_b32_e32 v9, 3, v9
	v_lshlrev_b32_e32 v10, 6, v193
	v_lshlrev_b32_e32 v11, 6, v153
	v_lshlrev_b32_e32 v12, 6, v154
	v_lshlrev_b32_e32 v13, 6, v155
	v_lshl_add_u32 v22, v152, 7, s11
	v_lshl_add_u32 v24, v160, 7, s11
	v_lshl_add_u32 v26, v161, 7, s11
	v_lshl_add_u32 v27, v162, 7, s11
	v_lshl_add_u64 v[132:133], v[2:3], 0, s[8:9]
	s_mov_b64 s[8:9], 0xa008000
	v_and_b32_e32 v149, 24, v220
	v_lshl_add_u64 v[134:135], v[2:3], 0, s[8:9]
	v_add_u32_e32 v163, v1, v6
	v_add_u32_e32 v164, v1, v7
	v_add_u32_e32 v165, v1, v8
	v_add_u32_e32 v166, v1, v9
	v_add_u32_e32 v167, v4, v10
	v_add_u32_e32 v168, v4, v11
	v_add_u32_e32 v169, v4, v12
	v_add_u32_e32 v170, v4, v13
	v_lshlrev_b32_e32 v136, 1, v0
	s_movk_i32 s11, 0x4000
	s_mov_b32 s19, 0x41000000
	s_mov_b64 s[20:21], 0x80
	v_add_u32_e32 v171, v5, v14
	v_add_u32_e32 v172, v5, v15
	v_add_u32_e32 v173, v5, v16
	v_add_u32_e32 v174, v5, v17
	v_add_u32_e32 v175, v5, v18
	v_add_u32_e32 v176, v5, v19
	v_add_u32_e32 v177, v5, v20
	v_add_u32_e32 v178, v5, v21
	v_add_u32_e32 v179, v22, v23
	v_add_u32_e32 v180, v24, v25
	v_add_u32_e32 v181, v26, v23
	v_add_u32_e32 v182, v27, v28
	v_mov_b32_e32 v183, 0x3c3504f3
	v_mov_b32_e32 v184, 0x3c800000
	s_mov_b32 s28, s75
	s_mov_b32 s47, -1
	s_cmp_eq_u32 s98, 0
	s_cbranch_scc1 .LBB0_300
	s_cmp_eq_u32 s98, 2
	s_cbranch_scc1 .Lp23_resume
	s_mov_b32 s44, -1
	s_cmp_eq_u32 s98, 1
	s_cbranch_scc0 .Lp23_clsB
	s_mov_b32 s45, s75
	s_mul_i32 s46, s45, 0x4001
	s_lshr_b32 s46, s46, 16
	s_mul_i32 s46, s46, 4
	s_sub_u32 s45, s45, s46
	s_branch .LBB0_299

.Lattn_fast:
	s_add_i32 s16, s28, 0xfffffe00
	s_ashr_i32 s22, s28, 8
	s_lshr_b32 s8, s28, 2
	s_and_b32 s9, s28, 3
	s_lshr_b32 s16, s16, 7
	s_add_i32 s22, s22, 8
	s_cmpk_lt_i32 s28, 0x200
	s_cselect_b32 s24, 5, 4
	s_cselect_b32 s23, 31, 15
	s_cselect_b32 s16, s22, s16
	s_lshr_b32 s26, s28, s24
	s_and_b32 s8, s8, s23
	s_and_b32 s30, s26, 4
	s_or_b32 s27, s30, s9
	s_lshl_b32 s9, s16, 13
	s_lshl_b32 s8, s8, 8
	s_add_i32 s22, s9, 0xffff8000
	s_lshl_b32 s23, s16, 12
	s_add_i32 s29, s8, s18
	s_cmp_lt_i32 s16, 8
	s_cselect_b32 s8, s23, s22
	s_cselect_b32 s31, 12, 13
	s_add_i32 s29, s29, s8
	v_or_b32_e32 v0, s29, v189
	v_ashrrev_i32_e32 v1, 31, v0
	v_lshlrev_b64 v[0:1], 10, v[0:1]
	v_lshl_add_u64 v[0:1], s[62:63], 0, v[0:1]
	s_lshl_b32 s16, s27, 7
	v_lshl_add_u64 v[0:1], v[0:1], 0, s[16:17]
	v_lshlrev_b32_e32 v98, 1, v196
	v_lshl_add_u64 v[8:9], v[0:1], 0, v[98:99]
	s_lshl_b32 s26, s8, 8
	s_lshl_b32 s9, s30, 5
	s_add_u32 s9, s26, s9
	s_add_u32 s22, s64, s9
	s_addc_u32 s23, s65, 0
	s_add_i32 s9, s31, 5
	s_lshl_b32 s9, s30, s9
	s_add_u32 s9, s26, s9
	s_add_u32 s24, s72, s9
	s_addc_u32 s25, s73, 0
	v_lshl_add_u32 v210, v148, 8, v136
	s_add_i32 s9, s31, 1
	v_lshlrev_b32_e32 v211, s9, v148
	v_add_u32_e32 v211, v211, v136
	v_add_u32_e32 v206, v151, v156
	v_add_u32_e32 v207, v151, v157
	v_add_u32_e32 v208, v151, v158
	v_add_u32_e32 v209, v151, v159
	s_lshl_b32 s30, s27, 6
	s_lshl_b32 s33, 1, s31
	s_lshr_b32 s33, s33, 6
	s_add_i32 s16, s33, -1
	s_lshr_b32 s33, s33, 2
	s_mov_b32 s31, 5
	s_mov_b32 s48, 0
	s_cmp_lg_u32 s47, s28
	s_cbranch_scc1 .Lattn_nopre
	s_waitcnt vmcnt(0)
	v_mov_b32_e32 v74, v90
	v_mov_b32_e32 v75, v91
	v_mov_b32_e32 v76, v92
	v_mov_b32_e32 v77, v93
	v_mov_b32_e32 v78, v250
	v_mov_b32_e32 v79, v251
	v_mov_b32_e32 v80, v252
	v_mov_b32_e32 v81, v253
	v_mov_b32_e32 v82, v94
	v_mov_b32_e32 v83, v95
	v_mov_b32_e32 v84, v96
	v_mov_b32_e32 v85, v97
	v_mov_b32_e32 v86, v138
	v_mov_b32_e32 v87, v139
	v_mov_b32_e32 v88, v140
	v_mov_b32_e32 v89, v141
	s_mov_b32 s47, -1
	s_mov_b32 s48, 1
	s_branch .Lattn_prejoin
.Lattn_nopre:
	global_load_dwordx4 v[32:35], v210, s[22:23]
	s_add_u32 s26, s22, 0x4000
	s_addc_u32 s27, s23, 0
	global_load_dwordx4 v[36:39], v210, s[26:27]
	s_add_u32 s8, s22, 0x8000
	s_addc_u32 s9, s23, 0
	global_load_dwordx4 v[40:43], v210, s[8:9]
	global_load_dwordx4 v[44:47], v211, s[24:25]
	global_load_dwordx4 v[48:51], v211, s[24:25] offset:128
	global_load_dwordx4 v[74:77], v[8:9], off
	global_load_dwordx4 v[78:81], v[8:9], off offset:32
	global_load_dwordx4 v[82:85], v[8:9], off offset:64
	global_load_dwordx4 v[86:89], v[8:9], off offset:96
.Lattn_prejoin:
	s_add_u32 s26, s22, 0xc000
	s_addc_u32 s27, s23, 0
	global_load_dwordx4 v[90:93], v210, s[26:27]
	global_load_dwordx4 v[94:97], v211, s[24:25] offset:256
	s_add_u32 s8, s22, 0x10000
	s_addc_u32 s9, s23, 0
	global_load_dwordx4 v[250:253], v210, s[8:9]
	global_load_dwordx4 v[138:141], v211, s[24:25] offset:384
	v_mov_b32_e32 v72, 0
	v_mov_b32_e32 v73, 0
	v_mov_b32_e32 v16, 0
	v_mov_b32_e32 v17, 0
	v_mov_b32_e32 v18, 0
	v_mov_b32_e32 v19, 0
	v_mov_b32_e32 v20, 0
	v_mov_b32_e32 v21, 0
	v_mov_b32_e32 v22, 0
	v_mov_b32_e32 v23, 0
	v_mov_b32_e32 v24, 0
	v_mov_b32_e32 v25, 0
	v_mov_b32_e32 v26, 0
	v_mov_b32_e32 v27, 0
	v_mov_b32_e32 v28, 0
	v_mov_b32_e32 v29, 0
	v_mov_b32_e32 v30, 0
	v_mov_b32_e32 v31, 0
	v_mov_b32_e32 v0, 0
	v_mov_b32_e32 v1, 0
	v_mov_b32_e32 v2, 0
	v_mov_b32_e32 v3, 0
	v_mov_b32_e32 v4, 0
	v_mov_b32_e32 v5, 0
	v_mov_b32_e32 v6, 0
	v_mov_b32_e32 v7, 0
	v_mov_b32_e32 v8, 0
	v_mov_b32_e32 v9, 0
	v_mov_b32_e32 v10, 0
	v_mov_b32_e32 v11, 0
	v_mov_b32_e32 v12, 0
	v_mov_b32_e32 v13, 0
	v_mov_b32_e32 v14, 0
	v_mov_b32_e32 v15, 0
	s_cmp_eq_u32 s48, 1
	s_cbranch_scc1 .Lattn_prejoin2
	s_waitcnt vmcnt(12)
	ds_write_b128 v150, v[32:35]
	s_waitcnt vmcnt(11)
	ds_write_b128 v150, v[36:39] offset:16384
	s_waitcnt vmcnt(10)
	ds_write_b128 v150, v[40:43] offset:32768
	s_waitcnt vmcnt(9)
	ds_write_b128 v150, v[44:47] offset:8192
	s_waitcnt vmcnt(8)
	ds_write_b128 v150, v[48:51] offset:24576
.Lattn_prejoin2:
	s_waitcnt lgkmcnt(0)
	s_barrier
	ds_read_b128 v[218:221], v206
	ds_read_b128 v[226:229], v207
	ds_read_b128 v[234:237], v208
	s_waitcnt lgkmcnt(2)
	s_waitcnt vmcnt(7)
	v_mfma_f32_32x32x16_bf16 v[32:47], v[218:221], v[74:77], 0
	ds_read_b128 v[242:245], v209
	s_waitcnt lgkmcnt(2)
	s_waitcnt vmcnt(6)
	v_mfma_f32_32x32x16_bf16 v[32:47], v[226:229], v[78:81], v[32:47]
	ds_read_b128 v[218:221], v206 offset:4096
	s_waitcnt lgkmcnt(2)
	s_waitcnt vmcnt(5)
	v_mfma_f32_32x32x16_bf16 v[32:47], v[234:237], v[82:85], v[32:47]
	ds_read_b128 v[226:229], v207 offset:4096
	s_waitcnt lgkmcnt(2)
	s_waitcnt vmcnt(4)
	v_mfma_f32_32x32x16_bf16 v[32:47], v[242:245], v[86:89], v[32:47]
	ds_read_b128 v[234:237], v208 offset:4096
	s_nop 9
	s_waitcnt lgkmcnt(2)
	v_mfma_f32_32x32x16_bf16 v[48:63], v[218:221], v[74:77], 0
	ds_read_b128 v[242:245], v209 offset:4096
	v_exp_f32_e32 v32, v32
	v_exp_f32_e32 v33, v33
	v_add_f32_e32 v72, v72, v32
	v_add_f32_e32 v73, v73, v33
	v_cvt_pk_bf16_f32 v64, v32, v33
	v_exp_f32_e32 v34, v34
	v_exp_f32_e32 v35, v35
	s_waitcnt lgkmcnt(2)
	v_mfma_f32_32x32x16_bf16 v[48:63], v[226:229], v[78:81], v[48:63]
	ds_read_b128 v[218:221], v206 offset:16384
	v_add_f32_e32 v72, v72, v34
	v_add_f32_e32 v73, v73, v35
	v_cvt_pk_bf16_f32 v65, v34, v35
	v_exp_f32_e32 v36, v36
	v_exp_f32_e32 v37, v37
	ds_read_b128 v[222:225], v206 offset:8192
	v_add_f32_e32 v72, v72, v36
	v_add_f32_e32 v73, v73, v37
	v_cvt_pk_bf16_f32 v66, v36, v37
	v_exp_f32_e32 v38, v38
	v_exp_f32_e32 v39, v39
	s_waitcnt lgkmcnt(3)
	v_mfma_f32_32x32x16_bf16 v[48:63], v[234:237], v[82:85], v[48:63]
	ds_read_b128 v[226:229], v207 offset:16384
	v_add_f32_e32 v72, v72, v38
	v_add_f32_e32 v73, v73, v39
	v_cvt_pk_bf16_f32 v67, v38, v39
	v_exp_f32_e32 v40, v40
	v_exp_f32_e32 v41, v41
	ds_read_b128 v[230:233], v206 offset:12288
	v_add_f32_e32 v72, v72, v40
	v_add_f32_e32 v73, v73, v41
	v_cvt_pk_bf16_f32 v68, v40, v41
	v_exp_f32_e32 v42, v42
	v_exp_f32_e32 v43, v43
	s_waitcnt lgkmcnt(4)
	v_mfma_f32_32x32x16_bf16 v[48:63], v[242:245], v[86:89], v[48:63]
	ds_read_b128 v[234:237], v208 offset:16384
	v_add_f32_e32 v72, v72, v42
	v_add_f32_e32 v73, v73, v43
	v_cvt_pk_bf16_f32 v69, v42, v43
	v_exp_f32_e32 v44, v44
	v_exp_f32_e32 v45, v45
	ds_read_b128 v[238:241], v207 offset:8192
	v_add_f32_e32 v72, v72, v44
	v_add_f32_e32 v73, v73, v45
	v_cvt_pk_bf16_f32 v70, v44, v45
	v_exp_f32_e32 v46, v46
	v_exp_f32_e32 v47, v47

.Lattn_tail:
	s_lshl_b32 s16, s30, 1
	v_lshl_add_u64 v[186:187], v[102:103], 0, s[16:17]
	v_or_b32_e32 v210, s29, v152
	v_mov_b32_e32 v211, 0
	v_lshlrev_b64 v[210:211], 10, v[210:211]
	v_lshl_add_u64 v[210:211], v[186:187], 0, v[210:211]
	global_load_dwordx4 v[74:77], v[210:211], off
	v_or_b32_e32 v210, s29, v160
	v_mov_b32_e32 v211, 0
	v_lshlrev_b64 v[210:211], 10, v[210:211]
	v_lshl_add_u64 v[210:211], v[186:187], 0, v[210:211]
	global_load_dwordx4 v[78:81], v[210:211], off
	v_or_b32_e32 v210, s29, v161
	v_mov_b32_e32 v211, 0
	v_lshlrev_b64 v[210:211], 10, v[210:211]
	v_lshl_add_u64 v[210:211], v[186:187], 0, v[210:211]
	global_load_dwordx4 v[82:85], v[210:211], off
	v_or_b32_e32 v210, s29, v162
	v_mov_b32_e32 v211, 0
	v_lshlrev_b64 v[210:211], 10, v[210:211]
	v_lshl_add_u64 v[210:211], v[186:187], 0, v[210:211]
	global_load_dwordx4 v[86:89], v[210:211], off
	s_mov_b32 s47, -1
	s_cmp_eq_u32 s98, 0
	s_cbranch_scc1 .Lan_gen
	s_add_i32 s48, s44, 1
	s_cmp_eq_u32 s98, 3
	s_cbranch_scc1 .Lan_B
	s_cmp_gt_u32 s48, 3
	s_cbranch_scc1 .Lan_done
	s_cmp_eq_u32 s48, s45
	s_cbranch_scc1 .Lan_done
	s_mov_b32 s49, s48
	s_cmp_gt_u32 s48, s45
	s_cbranch_scc0 .Lan_set
	s_add_i32 s49, s49, -1
	s_branch .Lan_set
.Lan_B:
	s_cmp_gt_u32 s48, 8
	s_cbranch_scc1 .Lan_done
	s_add_i32 s49, s48, 3
	s_cmp_lt_u32 s48, s45
	s_cbranch_scc1 .Lan_set
	s_add_i32 s49, s48, 6
	s_sub_u32 s49, s49, s45
	s_cmp_lt_u32 s49, 12
	s_cbranch_scc1 .Lan_done
	s_add_i32 s49, s48, -3
.Lan_set:
	s_lshl_b32 s47, s49, 8
	s_add_i32 s47, s47, s75
	s_branch .Lan_done
.Lan_gen:
	s_add_i32 s49, s28, s68
	s_cmpk_gt_i32 s49, 0x5ff
	s_cbranch_scc1 .Lan_done
	s_mov_b32 s47, s49
.Lan_done:
	s_cmp_eq_u32 s47, -1
	s_cbranch_scc1 .Lpf_skip
	s_mov_b32 s46, s47
	s_add_i32 s34, s46, 0xfffffe00
	s_ashr_i32 s22, s46, 8
	s_lshr_b32 s8, s46, 2
	s_and_b32 s9, s46, 3
	s_lshr_b32 s34, s34, 7
	s_add_i32 s22, s22, 8
	s_cmpk_lt_i32 s46, 0x200
	s_cselect_b32 s24, 5, 4
	s_cselect_b32 s23, 31, 15
	s_cselect_b32 s34, s22, s34
	s_lshr_b32 s26, s46, s24
	s_and_b32 s8, s8, s23
	s_and_b32 s37, s26, 4
	s_or_b32 s27, s37, s9
	s_lshl_b32 s9, s34, 13
	s_lshl_b32 s8, s8, 8
	s_add_i32 s22, s9, 0xffff8000
	s_lshl_b32 s23, s34, 12
	s_add_i32 s36, s8, s18
	s_cmp_lt_i32 s34, 8
	s_cselect_b32 s8, s23, s22
	s_cselect_b32 s31, 12, 13
	s_add_i32 s36, s36, s8
	v_or_b32_e32 v34, s36, v189
	v_ashrrev_i32_e32 v35, 31, v34
	v_lshlrev_b64 v[34:35], 10, v[34:35]
	v_lshl_add_u64 v[34:35], s[62:63], 0, v[34:35]
	s_lshl_b32 s34, s27, 7
	s_mov_b32 s35, 0
	v_lshl_add_u64 v[34:35], v[34:35], 0, s[34:35]
	v_lshlrev_b32_e32 v38, 1, v196
	v_mov_b32_e32 v39, 0
	v_lshl_add_u64 v[36:37], v[34:35], 0, v[38:39]
	s_lshl_b32 s26, s8, 8
	s_lshl_b32 s9, s37, 5
	s_add_u32 s9, s26, s9
	s_add_u32 s22, s64, s9
	s_addc_u32 s23, s65, 0
	s_add_i32 s9, s31, 5
	s_lshl_b32 s9, s37, s9
	s_add_u32 s9, s26, s9
	s_add_u32 s24, s72, s9
	s_addc_u32 s25, s73, 0
	v_and_b32_e32 v33, 0x70, v150
	v_lshl_add_u32 v32, v148, 8, v33
	s_add_i32 s9, s31, 1
	v_lshlrev_b32_e32 v38, s9, v148
	v_add_u32_e32 v33, v38, v33
	s_lshl_b32 s49, s18, 5
	s_mov_b32 m0, s49
	s_nop 0
	global_load_lds_dwordx4 v32, s[22:23]
	s_add_u32 s26, s22, 0x4000
	s_addc_u32 s27, s23, 0
	s_add_i32 m0, s49, 0x4000
	s_nop 0
	global_load_lds_dwordx4 v32, s[26:27]
	s_add_u32 s8, s22, 0x8000
	s_addc_u32 s9, s23, 0
	s_add_i32 m0, s49, 0x8000
	s_nop 0
	global_load_lds_dwordx4 v32, s[8:9]
	s_add_i32 m0, s49, 0x2000
	s_nop 0
	global_load_lds_dwordx4 v33, s[24:25]
	s_add_u32 s26, s24, 0x80
	s_addc_u32 s27, s25, 0
	s_add_i32 m0, s49, 0x6000
	s_nop 0
	global_load_lds_dwordx4 v33, s[26:27]
	global_load_dwordx4 v[90:93], v[36:37], off
	global_load_dwordx4 v[250:253], v[36:37], off offset:32
	global_load_dwordx4 v[94:97], v[36:37], off offset:64
	global_load_dwordx4 v[138:141], v[36:37], off offset:96
.Lpf_skip:
	v_add_f32_e32 v72, v72, v46
	v_add_f32_e32 v73, v73, v47
	v_cvt_pk_bf16_f32 v71, v46, v47
	v_exp_f32_e32 v48, v48
	v_exp_f32_e32 v49, v49
	s_waitcnt lgkmcnt(4)
	v_mfma_f32_32x32x16_bf16 v[16:31], v[222:225], v[64:67], v[16:31]
	ds_read_b128 v[246:249], v207 offset:61440
	v_add_f32_e32 v72, v72, v48
	v_add_f32_e32 v73, v73, v49
	v_cvt_pk_bf16_f32 v198, v48, v49
	v_exp_f32_e32 v50, v50
	v_exp_f32_e32 v51, v51
	v_add_f32_e32 v72, v72, v50
	v_add_f32_e32 v73, v73, v51
	v_cvt_pk_bf16_f32 v199, v50, v51
	v_exp_f32_e32 v52, v52
	v_exp_f32_e32 v53, v53
	s_waitcnt lgkmcnt(3)
	v_mfma_f32_32x32x16_bf16 v[0:15], v[230:233], v[64:67], v[0:15]
	ds_read_b128 v[222:225], v208 offset:57344
	v_add_f32_e32 v72, v72, v52
	v_add_f32_e32 v73, v73, v53
	v_cvt_pk_bf16_f32 v200, v52, v53
	v_exp_f32_e32 v54, v54
	v_exp_f32_e32 v55, v55
	v_add_f32_e32 v72, v72, v54
	v_add_f32_e32 v73, v73, v55
	v_cvt_pk_bf16_f32 v201, v54, v55
	v_exp_f32_e32 v56, v56
	v_exp_f32_e32 v57, v57
	s_waitcnt lgkmcnt(2)
	v_mfma_f32_32x32x16_bf16 v[16:31], v[238:241], v[68:71], v[16:31]
	ds_read_b128 v[230:233], v208 offset:61440
	v_add_f32_e32 v72, v72, v56
	v_add_f32_e32 v73, v73, v57
	v_cvt_pk_bf16_f32 v202, v56, v57
	v_exp_f32_e32 v58, v58
	v_exp_f32_e32 v59, v59
	v_add_f32_e32 v72, v72, v58
	v_add_f32_e32 v73, v73, v59
	v_cvt_pk_bf16_f32 v203, v58, v59
	v_exp_f32_e32 v60, v60
	v_exp_f32_e32 v61, v61
	s_waitcnt lgkmcnt(2)
	v_mfma_f32_32x32x16_bf16 v[0:15], v[246:249], v[68:71], v[0:15]
	ds_read_b128 v[238:241], v209 offset:57344
	v_add_f32_e32 v72, v72, v60
	v_add_f32_e32 v73, v73, v61
	v_cvt_pk_bf16_f32 v204, v60, v61
	v_exp_f32_e32 v62, v62
	v_exp_f32_e32 v63, v63
	v_add_f32_e32 v72, v72, v62
	v_add_f32_e32 v73, v73, v63
	v_cvt_pk_bf16_f32 v205, v62, v63
	s_waitcnt lgkmcnt(2)
	v_mfma_f32_32x32x16_bf16 v[16:31], v[222:225], v[198:201], v[16:31]
	ds_read_b128 v[246:249], v209 offset:61440
	s_waitcnt lgkmcnt(2)
	v_mfma_f32_32x32x16_bf16 v[0:15], v[230:233], v[198:201], v[0:15]
	s_waitcnt lgkmcnt(1)
	v_mfma_f32_32x32x16_bf16 v[16:31], v[238:241], v[202:205], v[16:31]
	s_waitcnt lgkmcnt(0)
	v_mfma_f32_32x32x16_bf16 v[0:15], v[246:249], v[202:205], v[0:15]
	v_add_f32_e32 v72, v72, v73
	s_cmp_eq_u32 s47, -1
	s_cbranch_scc1 .Lattn_dr0
	s_waitcnt vmcnt(9) lgkmcnt(0)
	s_branch .Lattn_dr1
.Lattn_dr0:
	s_waitcnt vmcnt(0) lgkmcnt(0)
.Lattn_dr1:
	s_barrier
	ds_bpermute_b32 v40, v147, v72
	v_lshl_add_u64 v[32:33], v[104:105], 0, s[16:17]
	s_waitcnt lgkmcnt(0)
	v_add_f32_e32 v40, v72, v40
	v_div_scale_f32 v41, s[8:9], v40, v40, 1.0
	v_rcp_f32_e32 v42, v41
	v_div_scale_f32 v43, vcc, 1.0, v40, 1.0
	v_fma_f32 v44, -v41, v42, 1.0
	v_fmac_f32_e32 v42, v44, v42
	v_mul_f32_e32 v44, v43, v42
	v_fma_f32 v45, -v41, v44, v43
	v_fmac_f32_e32 v44, v45, v42
	v_fma_f32 v41, -v41, v44, v43
	v_div_fmas_f32 v41, v41, v42, v44
	v_div_fixup_f32 v40, v41, v40, 1.0
	v_pk_mul_f32 v[16:17], v[40:41], v[16:17] op_sel_hi:[0,1]
	v_pk_mul_f32 v[18:19], v[40:41], v[18:19] op_sel_hi:[0,1]
	v_pk_mul_f32 v[20:21], v[40:41], v[20:21] op_sel_hi:[0,1]
	v_pk_mul_f32 v[22:23], v[40:41], v[22:23] op_sel_hi:[0,1]
	v_pk_mul_f32 v[24:25], v[40:41], v[24:25] op_sel_hi:[0,1]
	v_pk_mul_f32 v[26:27], v[40:41], v[26:27] op_sel_hi:[0,1]
	v_pk_mul_f32 v[28:29], v[40:41], v[28:29] op_sel_hi:[0,1]
	v_pk_mul_f32 v[30:31], v[40:41], v[30:31] op_sel_hi:[0,1]
	v_pk_mul_f32 v[0:1], v[40:41], v[0:1] op_sel_hi:[0,1]
	v_pk_mul_f32 v[2:3], v[40:41], v[2:3] op_sel_hi:[0,1]
	v_pk_mul_f32 v[4:5], v[40:41], v[4:5] op_sel_hi:[0,1]
	v_pk_mul_f32 v[6:7], v[40:41], v[6:7] op_sel_hi:[0,1]
	v_pk_mul_f32 v[8:9], v[40:41], v[8:9] op_sel_hi:[0,1]
	v_pk_mul_f32 v[10:11], v[40:41], v[10:11] op_sel_hi:[0,1]
	v_pk_mul_f32 v[12:13], v[40:41], v[12:13] op_sel_hi:[0,1]
	v_pk_mul_f32 v[14:15], v[40:41], v[14:15] op_sel_hi:[0,1]
	v_cvt_pk_bf16_f32 v16, v16, v17
	v_cvt_pk_bf16_f32 v17, v18, v19
	v_cvt_pk_bf16_f32 v18, v20, v21
	v_cvt_pk_bf16_f32 v19, v22, v23
	v_cvt_pk_bf16_f32 v20, v24, v25
	v_cvt_pk_bf16_f32 v21, v26, v27
	v_cvt_pk_bf16_f32 v22, v28, v29
	v_cvt_pk_bf16_f32 v23, v30, v31
	v_cvt_pk_bf16_f32 v0, v0, v1
	v_cvt_pk_bf16_f32 v1, v2, v3
	v_cvt_pk_bf16_f32 v2, v4, v5
	v_cvt_pk_bf16_f32 v3, v6, v7
	v_cvt_pk_bf16_f32 v4, v8, v9
	v_cvt_pk_bf16_f32 v5, v10, v11
	v_cvt_pk_bf16_f32 v6, v12, v13
	v_cvt_pk_bf16_f32 v7, v14, v15
	ds_write_b64 v171, v[16:17]
	ds_write_b64 v172, v[18:19]
	ds_write_b64 v173, v[20:21]
	ds_write_b64 v174, v[22:23]
	ds_write_b64 v175, v[0:1]
	ds_write_b64 v176, v[2:3]
	ds_write_b64 v177, v[4:5]
	ds_write_b64 v178, v[6:7]
	ds_read_b128 v[8:11], v179
	ds_read_b128 v[12:15], v180
	ds_read_b128 v[24:27], v181
	ds_read_b128 v[28:31], v182
	s_waitcnt lgkmcnt(3)
	v_cndmask_b32_e64 v46, v10, v8, s[6:7]
	v_cndmask_b32_e64 v47, v11, v9, s[6:7]
	v_cndmask_b32_e64 v48, v8, v10, s[6:7]
	v_cndmask_b32_e64 v49, v9, v11, s[6:7]
	v_lshlrev_b32_e32 v50, 16, v46
	v_and_b32_e32 v51, 0xffff0000, v46
	v_lshlrev_b32_e32 v52, 16, v74
	v_and_b32_e32 v53, 0xffff0000, v74
	v_pk_mul_f32 v[50:51], v[52:53], v[50:51]
	v_cvt_pk_bf16_f32 v54, v50, v51
	v_lshlrev_b32_e32 v50, 16, v47
	v_and_b32_e32 v51, 0xffff0000, v47
	v_lshlrev_b32_e32 v52, 16, v75
	v_and_b32_e32 v53, 0xffff0000, v75
	v_pk_mul_f32 v[50:51], v[52:53], v[50:51]
	v_cvt_pk_bf16_f32 v55, v50, v51
	v_lshlrev_b32_e32 v50, 16, v48
	v_and_b32_e32 v51, 0xffff0000, v48
	v_lshlrev_b32_e32 v52, 16, v76
	v_and_b32_e32 v53, 0xffff0000, v76
	v_pk_mul_f32 v[50:51], v[52:53], v[50:51]
	v_cvt_pk_bf16_f32 v56, v50, v51
	v_lshlrev_b32_e32 v50, 16, v49
	v_and_b32_e32 v51, 0xffff0000, v49
	v_lshlrev_b32_e32 v52, 16, v77
	v_and_b32_e32 v53, 0xffff0000, v77
	v_pk_mul_f32 v[50:51], v[52:53], v[50:51]
	v_cvt_pk_bf16_f32 v57, v50, v51
	v_or_b32_e32 v60, s29, v152
	v_mov_b32_e32 v61, 0
	v_lshlrev_b64 v[60:61], 11, v[60:61]
	v_lshl_add_u64 v[58:59], v[32:33], 0, v[60:61]
	global_store_dwordx4 v[58:59], v[54:57], off
	s_nop 1
	s_waitcnt lgkmcnt(2)
	v_cndmask_b32_e64 v46, v14, v12, s[6:7]
	v_cndmask_b32_e64 v47, v15, v13, s[6:7]
	v_cndmask_b32_e64 v48, v12, v14, s[6:7]
	v_cndmask_b32_e64 v49, v13, v15, s[6:7]
	v_lshlrev_b32_e32 v50, 16, v46
	v_and_b32_e32 v51, 0xffff0000, v46
	v_lshlrev_b32_e32 v52, 16, v78
	v_and_b32_e32 v53, 0xffff0000, v78
	v_pk_mul_f32 v[50:51], v[52:53], v[50:51]
	v_cvt_pk_bf16_f32 v54, v50, v51
	v_lshlrev_b32_e32 v50, 16, v47
	v_and_b32_e32 v51, 0xffff0000, v47
	v_lshlrev_b32_e32 v52, 16, v79
	v_and_b32_e32 v53, 0xffff0000, v79
	v_pk_mul_f32 v[50:51], v[52:53], v[50:51]
	v_cvt_pk_bf16_f32 v55, v50, v51
	v_lshlrev_b32_e32 v50, 16, v48
	v_and_b32_e32 v51, 0xffff0000, v48
	v_lshlrev_b32_e32 v52, 16, v80
	v_and_b32_e32 v53, 0xffff0000, v80
	v_pk_mul_f32 v[50:51], v[52:53], v[50:51]
	v_cvt_pk_bf16_f32 v56, v50, v51
	v_lshlrev_b32_e32 v50, 16, v49
	v_and_b32_e32 v51, 0xffff0000, v49
	v_lshlrev_b32_e32 v52, 16, v81
	v_and_b32_e32 v53, 0xffff0000, v81
	v_pk_mul_f32 v[50:51], v[52:53], v[50:51]
	v_cvt_pk_bf16_f32 v57, v50, v51
	v_or_b32_e32 v60, s29, v160
	v_mov_b32_e32 v61, 0
	v_lshlrev_b64 v[60:61], 11, v[60:61]
	v_lshl_add_u64 v[58:59], v[32:33], 0, v[60:61]
	global_store_dwordx4 v[58:59], v[54:57], off
	s_nop 1
	s_waitcnt lgkmcnt(1)
	v_cndmask_b32_e64 v46, v26, v24, s[6:7]
	v_cndmask_b32_e64 v47, v27, v25, s[6:7]
	v_cndmask_b32_e64 v48, v24, v26, s[6:7]
	v_cndmask_b32_e64 v49, v25, v27, s[6:7]
	v_lshlrev_b32_e32 v50, 16, v46
	v_and_b32_e32 v51, 0xffff0000, v46
	v_lshlrev_b32_e32 v52, 16, v82
	v_and_b32_e32 v53, 0xffff0000, v82
	v_pk_mul_f32 v[50:51], v[52:53], v[50:51]
	v_cvt_pk_bf16_f32 v54, v50, v51
	v_lshlrev_b32_e32 v50, 16, v47
	v_and_b32_e32 v51, 0xffff0000, v47
	v_lshlrev_b32_e32 v52, 16, v83
	v_and_b32_e32 v53, 0xffff0000, v83
	v_pk_mul_f32 v[50:51], v[52:53], v[50:51]
	v_cvt_pk_bf16_f32 v55, v50, v51
	v_lshlrev_b32_e32 v50, 16, v48
	v_and_b32_e32 v51, 0xffff0000, v48
	v_lshlrev_b32_e32 v52, 16, v84
	v_and_b32_e32 v53, 0xffff0000, v84
	v_pk_mul_f32 v[50:51], v[52:53], v[50:51]
	v_cvt_pk_bf16_f32 v56, v50, v51
	v_lshlrev_b32_e32 v50, 16, v49
	v_and_b32_e32 v51, 0xffff0000, v49
	v_lshlrev_b32_e32 v52, 16, v85
	v_and_b32_e32 v53, 0xffff0000, v85
	v_pk_mul_f32 v[50:51], v[52:53], v[50:51]
	v_cvt_pk_bf16_f32 v57, v50, v51
	v_or_b32_e32 v60, s29, v161
	v_mov_b32_e32 v61, 0
	v_lshlrev_b64 v[60:61], 11, v[60:61]
	v_lshl_add_u64 v[58:59], v[32:33], 0, v[60:61]
	global_store_dwordx4 v[58:59], v[54:57], off
	s_nop 1
	s_waitcnt lgkmcnt(0)
	v_cndmask_b32_e64 v46, v30, v28, s[6:7]
	v_cndmask_b32_e64 v47, v31, v29, s[6:7]
	v_cndmask_b32_e64 v48, v28, v30, s[6:7]
	v_cndmask_b32_e64 v49, v29, v31, s[6:7]
	v_lshlrev_b32_e32 v50, 16, v46
	v_and_b32_e32 v51, 0xffff0000, v46
	v_lshlrev_b32_e32 v52, 16, v86
	v_and_b32_e32 v53, 0xffff0000, v86
	v_pk_mul_f32 v[50:51], v[52:53], v[50:51]
	v_cvt_pk_bf16_f32 v54, v50, v51
	v_lshlrev_b32_e32 v50, 16, v47
	v_and_b32_e32 v51, 0xffff0000, v47
	v_lshlrev_b32_e32 v52, 16, v87
	v_and_b32_e32 v53, 0xffff0000, v87
	v_pk_mul_f32 v[50:51], v[52:53], v[50:51]
	v_cvt_pk_bf16_f32 v55, v50, v51
	v_lshlrev_b32_e32 v50, 16, v48
	v_and_b32_e32 v51, 0xffff0000, v48
	v_lshlrev_b32_e32 v52, 16, v88
	v_and_b32_e32 v53, 0xffff0000, v88
	v_pk_mul_f32 v[50:51], v[52:53], v[50:51]
	v_cvt_pk_bf16_f32 v56, v50, v51
	v_lshlrev_b32_e32 v50, 16, v49
	v_and_b32_e32 v51, 0xffff0000, v49
	v_lshlrev_b32_e32 v52, 16, v89
	v_and_b32_e32 v53, 0xffff0000, v89
	v_pk_mul_f32 v[50:51], v[52:53], v[50:51]
	v_cvt_pk_bf16_f32 v57, v50, v51
	v_or_b32_e32 v60, s29, v162
	v_mov_b32_e32 v61, 0
	v_lshlrev_b64 v[60:61], 11, v[60:61]
	v_lshl_add_u64 v[58:59], v[32:33], 0, v[60:61]
	global_store_dwordx4 v[58:59], v[54:57], off
	s_nop 1
	s_branch .LBB0_299
